# scores phase remapped to group-local chunk-heads; barriers after P1 and P2 also XCD-local
# speedup vs baseline: 1.0312x; 1.0012x over previous
.LBB0_550:
	s_or_b64 exec, exec, s[4:5]
	s_mov_b64 s[12:13], s[0:1]
	s_and_b32 s8, s2, 7
	s_lshl_b32 s8, s8, 8
	s_lshr_b32 s9, s2, 3
	s_or_b32 s8, s8, s9
	s_waitcnt lgkmcnt(0)
	s_barrier
	v_mbcnt_lo_u32_b32 v44, -1, 0
	v_mbcnt_hi_u32_b32 v44, -1, v44
	s_cmpk_gt_i32 s8, 0x7ff
	v_add_u32_e32 v0, s33, v44
	s_nop 0
	v_readfirstlane_b32 s9, v0
	s_cbranch_scc1 .LBB0_558
	s_load_dwordx4 s[4:7], s[12:13], 0x98
	v_add_u32_e32 v1, 0x200, v0
	v_ashrrev_i32_e32 v32, 5, v0
	v_ashrrev_i32_e32 v34, 5, v1
	v_add_u32_e32 v1, 0x400, v0
	s_waitcnt lgkmcnt(0)
	s_add_u32 s12, s6, 0x8800000
	s_addc_u32 s13, s7, 0
	s_add_u32 s14, s6, 0x4800000
	s_addc_u32 s15, s7, 0
	s_lshl_b32 s6, s8, 3
	v_add_u32_e32 v0, 0x600, v0
	s_and_b32 s6, s6, 0x600
	v_ashrrev_i32_e32 v38, 5, v0
	s_add_u32 s16, s12, s6
	v_lshlrev_b32_e32 v0, 4, v44
	s_addc_u32 s17, s13, 0
	v_and_b32_e32 v42, 0x1f0, v0
	v_mov_b32_e32 v43, 0
	v_lshl_add_u64 v[8:9], s[16:17], 0, v[42:43]
	s_ashr_i32 s16, s8, 8
	s_ashr_i32 s17, s16, 31
	s_lshl_b32 s18, s8, 6
	s_lshl_b64 s[16:17], s[16:17], 12
	s_and_b32 s18, s18, 0xfc0
	v_ashrrev_i32_e32 v33, 31, v32
	s_or_b32 s16, s16, s18
	v_ashrrev_i32_e32 v35, 31, v34
	v_ashrrev_i32_e32 v36, 5, v1
	v_lshl_add_u64 v[0:1], s[16:17], 0, v[32:33]
	v_lshlrev_b64 v[16:17], 11, v[0:1]
	v_lshl_add_u64 v[0:1], s[16:17], 0, v[34:35]
	v_ashrrev_i32_e32 v37, 31, v36
	v_lshl_add_u64 v[10:11], v[8:9], 0, v[16:17]
	v_lshlrev_b64 v[18:19], 11, v[0:1]
	v_ashrrev_i32_e32 v39, 31, v38
	v_lshl_add_u64 v[12:13], v[8:9], 0, v[18:19]
	global_load_dwordx4 v[4:7], v[10:11], off
	global_load_dwordx4 v[0:3], v[12:13], off
	v_lshl_add_u64 v[10:11], s[16:17], 0, v[36:37]
	v_lshlrev_b64 v[24:25], 11, v[10:11]
	v_lshl_add_u64 v[10:11], s[16:17], 0, v[38:39]
	s_add_u32 s16, s14, s6
	s_addc_u32 s17, s15, 0
	v_lshlrev_b64 v[26:27], 11, v[10:11]
	v_lshl_add_u64 v[28:29], s[16:17], 0, v[42:43]
	v_lshl_add_u64 v[20:21], v[8:9], 0, v[24:25]
	v_lshl_add_u64 v[22:23], v[8:9], 0, v[26:27]
	v_lshl_add_u64 v[30:31], v[28:29], 0, v[16:17]
	v_lshl_add_u64 v[40:41], v[28:29], 0, v[18:19]
	global_load_dwordx4 v[8:11], v[20:21], off
	global_load_dwordx4 v[12:15], v[22:23], off
	s_nop 0
	global_load_dwordx4 v[20:23], v[30:31], off
	global_load_dwordx4 v[16:19], v[40:41], off
	v_lshl_add_u64 v[40:41], v[28:29], 0, v[24:25]
	v_lshl_add_u64 v[46:47], v[28:29], 0, v[26:27]
	global_load_dwordx4 v[24:27], v[40:41], off
	global_load_dwordx4 v[28:31], v[46:47], off
	s_ashr_i32 s6, s9, 3
	v_and_b32_e32 v45, 15, v44
	v_bfe_u32 v52, v44, 4, 2
	v_add_u32_e32 v72, 0, v42
	v_lshl_add_u64 v[40:41], s[14:15], 0, v[42:43]
	v_lshl_add_u64 v[42:43], s[12:13], 0, v[42:43]
	v_bfi_b32 v44, -16, s6, v44
	s_movk_i32 s13, 0x210
	s_and_b32 s12, s6, -16
	v_mul_lo_u32 v44, v44, s13
	s_lshr_b32 s9, s9, 1
	v_add_u32_e32 v73, 0, v44
	v_and_or_b32 v53, s9, 32, v45
	v_lshl_or_b32 v44, v52, 2, s12
	v_or_b32_e32 v45, 16, v53
	v_sub_u32_e32 v46, v53, v44
	v_not_b32_e32 v60, 63
	v_lshl_add_u32 v46, v46, 1, v60
	v_sub_u32_e32 v48, v45, v44
	v_cvt_f32_i32_e32 v46, v46
	v_lshl_add_u32 v48, v48, 1, v60
	v_cvt_f32_i32_e32 v48, v48
	v_mov_b32_e32 v47, 0xc2800000
	v_cmp_gt_i32_e32 vcc, v53, v44
	s_ashr_i32 s9, s8, 31
	v_mad_u32_u24 v75, v53, s13, 0
	v_cndmask_b32_e32 v61, v47, v46, vcc
	v_cmp_gt_i32_e32 vcc, v45, v44
	v_or_b32_e32 v46, 1, v44
	v_sub_u32_e32 v49, v45, v46
	v_cndmask_b32_e32 v62, v47, v48, vcc
	v_sub_u32_e32 v48, v53, v46
	v_lshl_add_u32 v48, v48, 1, v60
	v_cvt_f32_i32_e32 v48, v48
	v_lshl_add_u32 v49, v49, 1, v60
	v_cmp_gt_i32_e32 vcc, v53, v46
	v_cvt_f32_i32_e32 v49, v49
	v_mul_lo_u32 v69, v32, s13
	v_cndmask_b32_e32 v63, v47, v48, vcc
	v_cmp_gt_i32_e32 vcc, v45, v46
	v_or_b32_e32 v46, 2, v44
	v_sub_u32_e32 v48, v53, v46
	v_lshl_add_u32 v48, v48, 1, v60
	v_cvt_f32_i32_e32 v48, v48
	v_cndmask_b32_e32 v64, v47, v49, vcc
	v_sub_u32_e32 v49, v45, v46
	v_lshl_add_u32 v49, v49, 1, v60
	v_cvt_f32_i32_e32 v49, v49
	v_cmp_gt_i32_e32 vcc, v53, v46
	v_mul_lo_u32 v77, v34, s13
	v_mul_lo_u32 v78, v36, s13
	v_cndmask_b32_e32 v65, v47, v48, vcc
	v_cmp_gt_i32_e32 vcc, v45, v46
	v_or_b32_e32 v46, 3, v44
	v_sub_u32_e32 v48, v53, v46
	v_lshl_add_u32 v48, v48, 1, v60
	v_cndmask_b32_e32 v66, v47, v49, vcc
	v_cvt_f32_i32_e32 v48, v48
	v_sub_u32_e32 v49, v45, v46
	v_mul_lo_u32 v79, v38, s13
	v_lshl_add_u32 v49, v49, 1, v60
	s_lshl_b64 s[12:13], s[8:9], 13
	v_cvt_f32_i32_e32 v49, v49
	s_add_u32 s4, s4, s12
	v_cmp_gt_i32_e32 vcc, v53, v46
	s_addc_u32 s5, s5, s13
	s_lshl_b32 s6, s6, 6
	v_cndmask_b32_e32 v67, v47, v48, vcc
	v_lshlrev_b32_e32 v48, 6, v44
	s_and_b32 s6, s6, 0xfffffc00
	v_lshlrev_b32_e32 v74, 4, v52
	v_lshlrev_b32_e32 v76, 3, v52
	v_cmp_gt_i32_e32 vcc, v45, v46
	v_or_b32_e32 v44, 0xc0, v48
	v_or_b32_e32 v46, 0x80, v48
	v_or_b32_e32 v48, 64, v48
	v_lshl_or_b32 v52, v52, 8, s6
	v_cndmask_b32_e32 v68, v47, v49, vcc
	v_ashrrev_i32_e32 v45, 31, v44
	v_or_b32_e32 v44, v44, v53
	v_mov_b64_e32 v[50:51], 0x4000020
	v_ashrrev_i32_e32 v47, 31, v46
	v_or_b32_e32 v46, v46, v53
	v_ashrrev_i32_e32 v49, 31, v48
	v_or_b32_e32 v48, v48, v53
	v_ashrrev_i32_e32 v59, 31, v52
	v_or_b32_e32 v58, v52, v53
	v_lshl_add_u64 v[44:45], v[44:45], 1, v[50:51]
	v_lshl_add_u64 v[46:47], v[46:47], 1, v[50:51]
	v_lshl_add_u64 v[48:49], v[48:49], 1, v[50:51]
	v_lshl_add_u64 v[50:51], v[58:59], 1, v[50:51]
	v_ashrrev_i32_e32 v59, 31, v58
	v_mov_b64_e32 v[70:71], 0x4000000
	v_lshl_add_u64 v[52:53], v[58:59], 1, v[70:71]
	v_or_b32_e32 v54, 64, v58
	v_or_b32_e32 v56, 0x80, v58
	v_or_b32_e32 v58, 0xc0, v58
	v_ashrrev_i32_e32 v55, 31, v54
	v_ashrrev_i32_e32 v57, 31, v56
	v_ashrrev_i32_e32 v59, 31, v58
	s_mov_b32 s7, 0
	v_lshl_add_u64 v[54:55], v[54:55], 1, v[70:71]
	v_lshl_add_u64 v[56:57], v[56:57], 1, v[70:71]
	v_lshl_add_u64 v[58:59], v[58:59], 1, v[70:71]
	v_add_u32_e32 v69, v72, v69
	v_add_u32_e32 v70, v72, v77
	v_add_u32_e32 v71, v72, v78
	v_add_u32_e32 v72, v72, v79
	v_add_u32_e32 v73, v73, v74
	v_add_u32_e32 v74, v75, v76
	s_mov_b32 s9, 0xc2fc0000
	s_movk_i32 s16, 0x7fff
	v_mov_b32_e32 v75, 0xbbb906ce
	v_mov_b32_e32 v76, 0xbc3963dd
	v_mov_b32_e32 v77, 0x42800000
	s_branch .LBB0_554

.LBB0_553:
	ds_read_b128 v[80:83], v73
	ds_read_b128 v[88:91], v73 offset:64
	v_add_u32_e32 v79, 0x8000, v74
	v_add_u32_e32 v128, 0xa000, v74
	ds_read2_b64 v[84:87], v79 offset0:128 offset1:132
	ds_read2_b64 v[92:95], v128 offset0:160 offset1:164
	s_waitcnt lgkmcnt(1)
	v_mfma_f32_16x16x32_bf16 v[84:87], v[80:83], v[84:87], 0
	s_waitcnt lgkmcnt(0)
	v_mfma_f32_16x16x32_bf16 v[80:83], v[80:83], v[92:95], 0
	ds_read2_b64 v[92:95], v79 offset0:136 offset1:140
	ds_read2_b64 v[96:99], v128 offset0:168 offset1:172
	s_waitcnt lgkmcnt(1)
	v_mfma_f32_16x16x32_bf16 v[84:87], v[88:91], v[92:95], v[84:87]
	ds_read_b128 v[92:95], v73 offset:128
	s_waitcnt lgkmcnt(1)
	v_mfma_f32_16x16x32_bf16 v[80:83], v[88:91], v[96:99], v[80:83]
	ds_read2_b64 v[88:91], v79 offset0:144 offset1:148
	ds_read_b128 v[96:99], v73 offset:192
	ds_read2_b64 v[100:103], v128 offset0:176 offset1:180
	s_waitcnt lgkmcnt(2)
	v_mfma_f32_16x16x32_bf16 v[84:87], v[92:95], v[88:91], v[84:87]
	ds_read2_b64 v[88:91], v79 offset0:152 offset1:156
	ds_read2_b64 v[104:107], v128 offset0:184 offset1:188
	ds_read2_b64 v[108:111], v79 offset0:160 offset1:164
	s_waitcnt lgkmcnt(3)
	v_mfma_f32_16x16x32_bf16 v[80:83], v[92:95], v[100:103], v[80:83]
	ds_read2_b64 v[92:95], v128 offset0:192 offset1:196
	ds_read_b128 v[100:103], v73 offset:256
	ds_read_b128 v[112:115], v73 offset:320
	s_waitcnt lgkmcnt(5)
	v_mfma_f32_16x16x32_bf16 v[84:87], v[96:99], v[88:91], v[84:87]
	ds_read2_b64 v[88:91], v79 offset0:168 offset1:172
	ds_read2_b64 v[116:119], v128 offset0:200 offset1:204
	ds_read2_b64 v[120:123], v79 offset0:176 offset1:180
	s_waitcnt lgkmcnt(4)
	v_mfma_f32_16x16x32_bf16 v[84:87], v[100:103], v[108:111], v[84:87]
	s_waitcnt lgkmcnt(2)
	v_mfma_f32_16x16x32_bf16 v[84:87], v[112:115], v[88:91], v[84:87]
	v_mfma_f32_16x16x32_bf16 v[80:83], v[96:99], v[104:107], v[80:83]
	ds_read_b128 v[96:99], v73 offset:384
	ds_read_b128 v[104:107], v73 offset:448
	ds_read2_b64 v[124:127], v79 offset0:184 offset1:188
	v_mul_f32_e32 v79, v61, v78
	v_cmp_gt_f32_e32 vcc, s9, v79
	s_waitcnt lgkmcnt(2)
	v_mfma_f32_16x16x32_bf16 v[84:87], v[96:99], v[120:123], v[84:87]
	v_cndmask_b32_e32 v88, 0, v77, vcc
	v_fmac_f32_e32 v88, v61, v78
	v_exp_f32_e32 v129, v88
	s_waitcnt lgkmcnt(0)
	v_mfma_f32_16x16x32_bf16 v[84:87], v[104:107], v[124:127], v[84:87]
	v_cndmask_b32_e32 v79, 0, v60, vcc
	ds_read2_b64 v[88:91], v128 offset0:208 offset1:212
	ds_read2_b64 v[108:111], v128 offset0:216 offset1:220
	v_ldexp_f32 v79, v129, v79
	v_mfma_f32_16x16x32_bf16 v[80:83], v[100:103], v[92:95], v[80:83]
	s_nop 2
	v_mul_f32_e32 v79, v79, v84
	v_bfe_u32 v84, v79, 16, 1
	v_add3_u32 v79, v79, v84, s16
	v_mul_f32_e32 v84, v62, v78
	v_cmp_gt_f32_e32 vcc, s9, v84
	v_mfma_f32_16x16x32_bf16 v[80:83], v[112:115], v[116:119], v[80:83]
	s_nop 0
	v_cndmask_b32_e32 v92, 0, v77, vcc
	v_fmac_f32_e32 v92, v62, v78
	v_exp_f32_e32 v92, v92
	s_waitcnt lgkmcnt(1)
	v_mfma_f32_16x16x32_bf16 v[80:83], v[96:99], v[88:91], v[80:83]
	v_cndmask_b32_e32 v84, 0, v60, vcc
	v_lshl_add_u64 v[88:89], s[4:5], 0, v[52:53]
	global_store_short_d16_hi v[88:89], v79, off
	v_ldexp_f32 v79, v92, v84
	v_mul_f32_e32 v84, v63, v78
	s_waitcnt lgkmcnt(0)
	v_mfma_f32_16x16x32_bf16 v[80:83], v[104:107], v[108:111], v[80:83]
	v_cmp_gt_f32_e32 vcc, s9, v84
	s_nop 1
	v_cndmask_b32_e32 v88, 0, v77, vcc
	v_fmac_f32_e32 v88, v63, v78
	v_exp_f32_e32 v90, v88
	s_nop 1
	v_mul_f32_e32 v79, v79, v80
	v_bfe_u32 v80, v79, 16, 1
	v_cndmask_b32_e32 v84, 0, v60, vcc
	v_add3_u32 v79, v79, v80, s16
	v_lshl_add_u64 v[88:89], s[4:5], 0, v[50:51]
	global_store_short_d16_hi v[88:89], v79, off
	v_ldexp_f32 v79, v90, v84
	v_mul_f32_e32 v84, v64, v78
	v_cmp_gt_f32_e32 vcc, s9, v84
	v_mul_f32_e32 v79, v79, v85
	v_bfe_u32 v80, v79, 16, 1
	v_cndmask_b32_e32 v84, 0, v77, vcc
	v_fmac_f32_e32 v84, v64, v78
	v_exp_f32_e32 v89, v84
	v_cndmask_b32_e32 v88, 0, v60, vcc
	v_add3_u32 v79, v79, v80, s16
	v_lshl_add_u64 v[84:85], s[4:5], 0, v[54:55]
	global_store_short_d16_hi v[84:85], v79, off
	v_ldexp_f32 v79, v89, v88
	v_mul_f32_e32 v79, v79, v81
	v_mul_f32_e32 v81, v65, v78
	v_cmp_gt_f32_e32 vcc, s9, v81
	v_bfe_u32 v80, v79, 16, 1
	v_add3_u32 v79, v79, v80, s16
	v_cndmask_b32_e32 v81, 0, v77, vcc
	v_fmac_f32_e32 v81, v65, v78
	v_exp_f32_e32 v85, v81
	v_lshl_add_u64 v[80:81], s[4:5], 0, v[48:49]
	global_store_short_d16_hi v[80:81], v79, off
	v_mul_f32_e32 v81, v66, v78
	v_cndmask_b32_e32 v84, 0, v60, vcc
	v_cmp_gt_f32_e32 vcc, s9, v81
	v_ldexp_f32 v79, v85, v84
	v_mul_f32_e32 v79, v79, v86
	v_cndmask_b32_e32 v81, 0, v77, vcc
	v_fmac_f32_e32 v81, v66, v78
	v_bfe_u32 v80, v79, 16, 1
	v_exp_f32_e32 v85, v81
	v_add3_u32 v79, v79, v80, s16
	v_lshl_add_u64 v[80:81], s[4:5], 0, v[56:57]
	global_store_short_d16_hi v[80:81], v79, off
	v_mul_f32_e32 v81, v67, v78
	v_cndmask_b32_e32 v84, 0, v60, vcc
	v_cmp_gt_f32_e32 vcc, s9, v81
	v_ldexp_f32 v79, v85, v84
	v_mul_f32_e32 v79, v79, v82
	v_cndmask_b32_e32 v81, 0, v77, vcc
	v_fmac_f32_e32 v81, v67, v78
	v_bfe_u32 v80, v79, 16, 1
	v_exp_f32_e32 v84, v81
	v_add3_u32 v79, v79, v80, s16
	v_lshl_add_u64 v[80:81], s[4:5], 0, v[46:47]
	global_store_short_d16_hi v[80:81], v79, off
	v_mul_f32_e32 v81, v68, v78
	v_cndmask_b32_e32 v82, 0, v60, vcc
	v_cmp_gt_f32_e32 vcc, s9, v81
	v_ldexp_f32 v79, v84, v82
	v_mul_f32_e32 v79, v79, v87
	v_cndmask_b32_e32 v82, 0, v77, vcc
	v_fmac_f32_e32 v82, v68, v78
	v_exp_f32_e32 v82, v82
	v_bfe_u32 v80, v79, 16, 1
	v_cndmask_b32_e32 v81, 0, v60, vcc
	v_add3_u32 v80, v79, v80, s16
	v_lshl_add_u64 v[78:79], s[4:5], 0, v[58:59]
	global_store_short_d16_hi v[78:79], v80, off
	v_ldexp_f32 v78, v82, v81
	v_mul_f32_e32 v78, v78, v83
	v_bfe_u32 v79, v78, 16, 1
	v_add3_u32 v80, v78, v79, s16
	v_lshl_add_u64 v[78:79], s[4:5], 0, v[44:45]
	s_add_u32 s4, s4, 0x40000
	s_addc_u32 s5, s5, 0
	s_andn2_b64 vcc, exec, s[12:13]
	global_store_short_d16_hi v[78:79], v80, off
	s_cbranch_vccz .LBB0_558
.LBB0_554:
	s_mov_b32 s14, s8
	s_addk_i32 s8, 0x20
	s_and_b32 s15, s14, 0xff
	s_cmpk_gt_i32 s15, 0xdf
	s_cselect_b64 s[12:13], -1, 0
	s_cmpk_lt_i32 s15, 0xe0
	s_cselect_b32 s6, s8, 0x7ff
	s_ashr_i32 s18, s6, 8
	s_ashr_i32 s19, s18, 31
	s_lshl_b32 s15, s6, 6
	s_lshl_b64 s[18:19], s[18:19], 12
	s_and_b32 s15, s15, 0xfc0
	s_or_b32 s18, s18, s15
	s_lshl_b32 s6, s6, 3
	s_waitcnt vmcnt(63) expcnt(7) lgkmcnt(15)
	s_barrier
	s_waitcnt vmcnt(3)
	ds_write_b128 v69, v[20:23]
	ds_write_b128 v69, v[4:7] offset:33792
	s_waitcnt vmcnt(2)
	ds_write_b128 v70, v[16:19]
	ds_write_b128 v70, v[0:3] offset:33792
	s_waitcnt vmcnt(1)
	ds_write_b128 v71, v[24:27]
	ds_write_b128 v71, v[8:11] offset:33792
	s_waitcnt vmcnt(0)
	ds_write_b128 v72, v[28:31]
	ds_write_b128 v72, v[12:15] offset:33792
	s_and_b32 s6, s6, 0x600
	v_lshl_add_u64 v[0:1], s[18:19], 0, v[32:33]
	v_lshl_add_u64 v[12:13], v[40:41], 0, s[6:7]
	v_lshl_add_u64 v[14:15], v[42:43], 0, s[6:7]
	v_lshlrev_b64 v[0:1], 11, v[0:1]
	v_lshl_add_u64 v[2:3], v[12:13], 0, v[0:1]
	v_lshl_add_u64 v[0:1], v[14:15], 0, v[0:1]
	global_load_dwordx4 v[20:23], v[2:3], off
	global_load_dwordx4 v[4:7], v[0:1], off
	v_lshl_add_u64 v[0:1], s[18:19], 0, v[34:35]
	v_lshlrev_b64 v[0:1], 11, v[0:1]
	v_lshl_add_u64 v[8:9], v[12:13], 0, v[0:1]
	v_lshl_add_u64 v[10:11], v[14:15], 0, v[0:1]
	global_load_dwordx4 v[16:19], v[8:9], off
	global_load_dwordx4 v[0:3], v[10:11], off
	v_lshl_add_u64 v[8:9], s[18:19], 0, v[36:37]
	v_lshlrev_b64 v[8:9], 11, v[8:9]
	v_lshl_add_u64 v[28:29], v[12:13], 0, v[8:9]
	v_lshl_add_u64 v[30:31], v[14:15], 0, v[8:9]
	global_load_dwordx4 v[24:27], v[28:29], off
	global_load_dwordx4 v[8:11], v[30:31], off
	v_lshl_add_u64 v[28:29], s[18:19], 0, v[38:39]
	v_lshlrev_b64 v[28:29], 11, v[28:29]
	v_lshl_add_u64 v[78:79], v[12:13], 0, v[28:29]
	v_lshl_add_u64 v[80:81], v[14:15], 0, v[28:29]
	global_load_dwordx4 v[28:31], v[78:79], off
	global_load_dwordx4 v[12:15], v[80:81], off
	s_bfe_u32 s6, s14, 0x20006
	s_cmp_lt_i32 s6, 1
	v_mov_b32_e32 v78, 0xbd3b9ca6
	s_waitcnt lgkmcnt(0)
	s_barrier
	s_cbranch_scc1 .LBB0_553
	s_cmp_eq_u32 s6, 1
	s_cbranch_scc1 .LBB0_557
	s_cmp_eq_u32 s6, 2
	s_cselect_b64 vcc, -1, 0
	v_cndmask_b32_e32 v78, v75, v76, vcc
	s_cbranch_execnz .LBB0_553
	s_branch .LBB0_552
